# c54 + S2 (token-0 GLA mixer) tail: all seven tail loads issued together right after the reduce barrier, one wait instead of four serialized load latencies; late K-loop offset preserved
# baseline (speedup 1.0000x reference)
; DI float silu_f(float x) { return x / (1.0f + __expf(-x)); }
; DI void tok0_mix_gla(ldsp lds, const Params& p, const float* P, float* BRo, int task, int tid, int wid, int lane) {
;     ...
;     if (tid < 64) BRo[(size_t)b * 1024 + 768 + hm * 64 + tid] = OUT[tid] * silu_f(pr[GA_GATE + 768 + hm * 64 + tid]);
;     const float* qp = pr + hm * 96; const float* kp = pr + GA_K + hm * 96;
;     const float a = wave_sum(qp[lane] * kp[lane] + (lane < 32 ? qp[64 + lane] * kp[64 + lane] : 0.f)) * 0.10206207261596575f;
;     float ve = 0.f;
;     if (tid < 192) ve = pr[GA_V + hm * 192 + tid];
;     const float sq = wave_sum(ve * ve);
;     if (lane == 0 && wid < 3) R3[wid] = sq;
;     __syncthreads();
;     const float msv = (R3[0] + R3[1] + R3[2]) * (1.0f / 192.0f);
;     const float rs = rsqrtf(a * a * msv + 1e-6f);
;     if (tid < 192) BRo[(size_t)b * 1024 + hm * 192 + tid] = a * ve * rs * p.gla_norm_w[tid] * silu_f(pr[GA_GATE + hm * 192 + tid]);
.LBB0_850:
	s_or_b64 exec, exec, s[26:27]
	s_waitcnt lgkmcnt(0)
	s_barrier
	s_mul_i32 s0, s37, 0x180
	s_add_u32 s22, s48, s0
	s_addc_u32 s23, s49, 0
	s_mul_i32 s0, s37, 0xc0
	global_load_dword v1, v90, s[22:23]
	global_load_dword v2, v90, s[22:23] offset:1536
	v_mov_b32_e32 v0, 0
	v_mov_b32_e32 v3, 0
	v_mov_b32_e32 v4, 0
	s_mov_b64 s[98:99], exec
	s_and_b64 exec, s[98:99], s[42:43]
	v_mov_b32_e32 v91, v12
	v_lshl_add_u64 v[226:227], s[22:23], 0, v[90:91]
	global_load_dword v3, v[226:227], off offset:256
	global_load_dword v4, v[226:227], off offset:1792
	s_and_b64 exec, s[98:99], s[44:45]
	v_lshl_add_u64 v[226:227], v[32:33], 0, s[0:1]
	v_lshl_add_u64 v[226:227], v[226:227], 2, s[48:49]
	global_load_dword v0, v[226:227], off offset:3072
	v_add_u32_e32 v228, s0, v106
	v_ashrrev_i32_e32 v229, 31, v228
	v_lshl_add_u64 v[228:229], v[228:229], 2, s[48:49]
	global_load_dword v5, v[228:229], off
	global_load_dword v8, v[82:83], off
	s_mov_b64 exec, s[98:99]
	s_and_saveexec_b64 s[26:27], s[38:39]
	s_cbranch_execz .LBB0_852
	v_add_u32_e32 v242, s51, v105
	v_ashrrev_i32_e32 v243, 31, v242
	v_lshl_add_u64 v[242:243], v[242:243], 2, s[48:49]
	global_load_dword v242, v[242:243], off
	ds_read_b32 v244, v104
	v_readlane_b32 s30, v251, 27
	v_readlane_b32 s31, v251, 28
	s_waitcnt vmcnt(0)
	v_mul_f32_e32 v243, 0xbfb8aa3b, v242
	v_exp_f32_e32 v243, v243
	s_nop 0
	v_add_f32_e32 v243, 1.0, v243
	v_div_scale_f32 v245, s[22:23], v243, v243, v242
	v_rcp_f32_e32 v246, v245
	s_lshl_b64 s[22:23], s[46:47], 12
	s_add_u32 s0, s30, s22
	s_addc_u32 s23, s31, s23
	v_fma_f32 v247, -v245, v246, 1.0
	v_fmac_f32_e32 v246, v247, v246
	v_div_scale_f32 v247, vcc, v242, v243, v242
	v_mul_f32_e32 v248, v247, v246
	v_fma_f32 v249, -v245, v248, v247
	v_fmac_f32_e32 v248, v249, v246
	v_fma_f32 v245, -v245, v248, v247
	v_div_fmas_f32 v245, v245, v246, v248
	s_add_u32 s22, s0, s50
	v_div_fixup_f32 v242, v245, v243, v242
	s_addc_u32 s23, s23, 0
	s_waitcnt lgkmcnt(0)
	v_mul_f32_e32 v244, v244, v242
	v_lshl_add_u64 v[242:243], v[32:33], 2, s[22:23]
	global_store_dword v[242:243], v244, off offset:3072
.LBB0_852:
	s_or_b64 exec, exec, s[26:27]
	s_waitcnt vmcnt(0)
	v_mul_f32_e32 v3, v3, v4
	v_fmac_f32_e32 v3, v1, v2
	ds_bpermute_b32 v1, v97, v3
	s_mul_i32 s0, s37, 0xc0
	s_waitcnt lgkmcnt(0)
	v_add_f32_e32 v1, v3, v1
	ds_bpermute_b32 v2, v98, v1
	s_waitcnt lgkmcnt(0)
	v_add_f32_e32 v1, v1, v2
	ds_bpermute_b32 v2, v99, v1
	s_waitcnt lgkmcnt(0)
	v_add_f32_e32 v1, v1, v2
	ds_bpermute_b32 v2, v100, v1
	s_waitcnt lgkmcnt(0)
	v_add_f32_e32 v1, v1, v2
	ds_bpermute_b32 v2, v101, v1
	s_waitcnt lgkmcnt(0)
	v_add_f32_e32 v1, v1, v2
	ds_bpermute_b32 v2, v102, v1
	s_waitcnt vmcnt(0)
	v_mul_f32_e32 v3, v0, v0
	ds_bpermute_b32 v3, v97, v3
	s_waitcnt lgkmcnt(0)
	v_fmac_f32_e32 v3, v0, v0
	ds_bpermute_b32 v4, v98, v3
	s_waitcnt lgkmcnt(0)
	v_add_f32_e32 v3, v3, v4
	ds_bpermute_b32 v4, v99, v3
	s_waitcnt lgkmcnt(0)
	v_add_f32_e32 v3, v3, v4
	ds_bpermute_b32 v4, v100, v3
	s_waitcnt lgkmcnt(0)
	v_add_f32_e32 v3, v3, v4
	ds_bpermute_b32 v4, v101, v3
	s_waitcnt lgkmcnt(0)
	v_add_f32_e32 v3, v3, v4
	ds_bpermute_b32 v4, v102, v3
	s_and_saveexec_b64 s[22:23], s[18:19]
	s_cbranch_execz .LBB0_858
	s_waitcnt lgkmcnt(0)
	v_add_f32_e32 v3, v3, v4
	v_mov_b32_e32 v4, s17
	ds_write_b32 v4, v3
.LBB0_858:
	s_or_b64 exec, exec, s[22:23]
	s_waitcnt lgkmcnt(0)
	s_barrier
	s_and_saveexec_b64 s[26:27], s[44:45]
	s_cbranch_execz .LBB0_829
	v_add_f32_e32 v1, v1, v2
	s_add_i32 s30, 0, 0x10100
	v_mul_f32_e32 v6, 0x3dd105ec, v1
	v_mov_b32_e32 v1, s30
	ds_read_b96 v[2:4], v1
	v_mul_f32_e32 v9, v6, v0
	v_mov_b32_e32 v156, v6
	s_lshl_b64 s[22:23], s[46:47], 12
	v_readlane_b32 s30, v251, 27
	s_waitcnt lgkmcnt(0)
	v_add_f32_e32 v0, v2, v3
	v_add_f32_e32 v7, v0, v4
	v_pk_mul_f32 v[0:1], v[6:7], v[156:157]
	v_readlane_b32 s31, v251, 28
	v_fmaak_f32 v0, v0, v1, 0x358637bd
	v_mul_f32_e32 v1, 0x4b800000, v0
	v_cmp_gt_f32_e32 vcc, s33, v0
	s_add_u32 s22, s30, s22
	s_addc_u32 s23, s31, s23
	v_cndmask_b32_e32 v0, v0, v1, vcc
	v_rsq_f32_e32 v0, v0
	s_lshl_b32 s0, s0, 2
	s_add_u32 s22, s22, s0
	s_addc_u32 s23, s23, 0
	v_mul_f32_e32 v2, 0x45800000, v0
	v_cndmask_b32_e32 v0, v0, v2, vcc
	v_mul_f32_e32 v0, v9, v0
	s_waitcnt vmcnt(1)
	v_mul_f32_e32 v1, 0xbfb8aa3b, v5
	v_exp_f32_e32 v1, v1
	s_waitcnt vmcnt(0)
	v_mul_f32_e32 v0, v8, v0
	v_add_f32_e32 v1, 1.0, v1
	v_div_scale_f32 v2, s[30:31], v1, v1, v5
	v_rcp_f32_e32 v3, v2
	v_div_scale_f32 v4, vcc, v5, v1, v5
	v_fma_f32 v6, -v2, v3, 1.0
	v_fmac_f32_e32 v3, v6, v3
	v_mul_f32_e32 v6, v4, v3
	v_fma_f32 v7, -v2, v6, v4
	v_fmac_f32_e32 v6, v7, v3
	v_fma_f32 v2, -v2, v6, v4
	v_div_fmas_f32 v2, v2, v3, v6
	v_div_fixup_f32 v1, v2, v1, v5
	v_mul_f32_e32 v2, v1, v0
	v_lshl_add_u64 v[0:1], v[32:33], 2, s[22:23]
	global_store_dword v[0:1], v2, off
	s_branch .LBB0_829
.LBB0_860:
	s_nop 0
	s_nop 0
	s_mov_b64 s[22:23], 0
